# phase 9: second GEMM runs with reversed workgroup order (5 tiles per WG); phase-0 adaLN/silu loads batched; phase-0 conversion back to single tiles
# speedup vs baseline: 1.0098x; 1.0098x over previous
.LBB0_827:
	v_readlane_b32 s0, v254, 13
	v_readlane_b32 s1, v254, 14
	s_and_b64 vcc, exec, s[0:1]
	v_readfirstlane_b32 s3, v146
	s_cbranch_vccnz .LBB0_839
	s_sub_i32 s88, s68, s2
	s_add_i32 s88, s88, -1
	s_add_u32 s4, s34, 0x2e00000
	s_addc_u32 s5, s35, 0
	s_lshr_b32 s1, s83, 31
	s_ashr_i32 s7, s83, 8
	s_add_i32 s18, s7, s1
	s_mul_i32 s1, s18, 0x280
	s_sub_i32 s1, s88, s1
	s_bfe_u32 s7, s1, 0x3001c
	s_add_i32 s7, s1, s7
	s_sext_i32_i16 s8, s7
	s_and_b32 s7, s7, 0xfff8
	s_lshr_b32 s0, s3, 6
	s_sub_i32 s1, s1, s7
	s_lshr_b32 s9, s3, 8
	s_lshl_b32 s6, s0, 10
	s_ashr_i32 s19, s18, 31
	s_ashr_i32 s8, s8, 3
	s_sext_i32_i16 s7, s1
	s_cmp_lt_i32 s7, 0
	s_movk_i32 s7, 0x51
	s_cselect_b32 s10, s7, 0x50
	s_mul_i32 s1, s10, s1
	s_add_i32 s1, s1, s8
	s_sext_i32_i16 s8, s1
	s_bfe_u32 s8, s8, 0x5001a
	s_add_i32 s8, s1, s8
	s_sext_i32_i16 s10, s8
	s_and_b32 s8, s8, 0xffe0
	s_sub_i32 s1, s1, s8
	s_bfe_i32 s8, s1, 0x80000
	s_bfe_u32 s8, s8, 0x3000c
	s_add_i32 s11, s1, s8
	s_bfe_i32 s8, s11, 0x80000
	s_and_b32 s11, s11, 0xf8
	s_ashr_i32 s10, s10, 5
	s_sub_i32 s1, s1, s11
	s_lshl_b32 s10, s10, 3
	s_sext_i32_i16 s8, s8
	s_sext_i32_i8 s1, s1
	s_lshr_b32 s8, s8, 3
	s_add_i32 s22, s10, s1
	s_ashr_i32 s23, s22, 31
	s_bfe_i64 s[14:15], s[8:9], 0x100000
	s_lshl_b64 s[10:11], s[22:23], 18
	s_lshl_b64 s[12:13], s[18:19], 10
	s_lshl_b64 s[14:15], s[14:15], 18
	s_add_u32 s1, s4, s14
	s_addc_u32 s14, s5, s15
	s_add_u32 s50, s1, s12
	s_addc_u32 s51, s14, s13
	s_add_i32 s19, s6, 0
	s_add_i32 m0, s19, 0x10000
	v_lshl_or_b32 v134, v188, 10, v189
	global_load_lds_dwordx4 v130, s[50:51]
	s_add_i32 m0, s19, 0x12000
	s_add_u32 s1, s42, s10
	s_addc_u32 s10, s43, s11
	s_add_u32 s52, s1, s12
	global_load_lds_dwordx4 v128, s[50:51]
	s_addc_u32 s53, s10, s13
	s_mov_b32 m0, s19
	s_add_i32 s23, s19, 0x2000
	v_lshl_or_b32 v132, v191, 10, v189
	global_load_lds_dwordx4 v134, s[52:53]
	s_mov_b32 m0, s23
	s_add_u32 s10, s50, 0x20000
	global_load_lds_dwordx4 v132, s[52:53]
	s_addc_u32 s11, s51, 0
	s_add_i32 m0, s19, 0x14000
	v_mov_b32_e32 v131, 0
	global_load_lds_dwordx4 v130, s[10:11]
	s_add_i32 m0, s19, 0x16000
	v_mov_b32_e32 v129, v131
	global_load_lds_dwordx4 v128, s[10:11]
	s_add_u32 s10, s52, 0x20000
	s_addc_u32 s11, s53, 0
	s_add_i32 s26, s19, 0x4000
	s_mov_b32 m0, s26
	s_add_i32 s27, s19, 0x6000
	global_load_lds_dwordx4 v134, s[10:11]
	s_mov_b32 m0, s27
	v_mov_b32_e32 v135, v131
	global_load_lds_dwordx4 v132, s[10:11]
	v_mov_b32_e32 v133, v131
	s_mov_b32 s33, 0
	v_lshl_add_u64 v[6:7], s[50:51], 0, v[130:131]
	v_lshl_add_u64 v[4:5], s[50:51], 0, v[128:129]
	v_lshl_add_u64 v[2:3], s[52:53], 0, v[134:135]
	s_cmp_lg_u32 s9, 1
	v_lshl_add_u64 v[0:1], s[52:53], 0, v[132:133]
	s_cbranch_scc1 .LBB0_830
	s_barrier
.LBB0_830:
	s_lshl_b32 s0, s0, 5
	s_and_b32 s13, s0, 0x60
	s_mov_b64 s[0:1], 0x80
	s_add_i32 m0, s19, 0x18000
	v_lshl_add_u64 v[6:7], v[6:7], 0, s[0:1]
	s_ashr_i32 s56, s88, 31
	s_lshl_b32 s12, s9, 13
	s_waitcnt vmcnt(4)
	s_barrier
	global_load_lds_dwordx4 v[6:7], off
	v_lshl_add_u64 v[4:5], v[4:5], 0, s[0:1]
	s_add_i32 m0, s19, 0x1a000
	s_add_i32 s57, s19, 0x8000
	s_add_i32 s64, s19, 0xa000
	global_load_lds_dwordx4 v[4:5], off
	v_lshl_add_u64 v[2:3], v[2:3], 0, s[0:1]
	s_mov_b32 m0, s57
	s_add_u32 s10, s50, 0x20080
	global_load_lds_dwordx4 v[2:3], off
	v_lshl_add_u64 v[0:1], v[0:1], 0, s[0:1]
	s_mov_b32 m0, s64
	s_addc_u32 s11, s51, 0
	global_load_lds_dwordx4 v[0:1], off
	s_add_i32 m0, s19, 0x1c000
	v_lshl_add_u64 v[0:1], s[10:11], 0, v[130:131]
	global_load_lds_dwordx4 v[0:1], off
	v_lshl_add_u64 v[0:1], s[10:11], 0, v[128:129]
	s_add_i32 m0, s19, 0x1e000
	v_lshlrev_b32_e32 v2, 10, v185
	global_load_lds_dwordx4 v[0:1], off
	v_lshl_or_b32 v0, v181, 6, v182
	v_and_b32_e32 v1, 32, v165
	v_bitop3_b32 v0, v0, s12, v1 bitop3:0xde
	v_lshlrev_b32_e32 v1, 7, v146
	v_and_b32_e32 v1, 0x1c000, v1
	v_or3_b32 v1, v187, v1, v2
	v_add_u32_e32 v136, v1, v184
	v_lshlrev_b32_e32 v1, 3, v193
	s_waitcnt vmcnt(6)
	v_and_b32_e32 v1, 0x3c000, v1
	v_lshl_or_b32 v151, s13, 7, v183
	v_or3_b32 v1, v187, v1, v2
	s_add_i32 s71, 0, 0x10000
	s_add_i32 s72, 0, 0x14000
	s_sext_i32_i8 s77, s8
	v_lshl_or_b32 v145, s9, 6, v181
	s_ashr_i32 s65, s68, 31
	s_mov_b32 s70, s68
	v_or_b32_e32 v153, s13, v180
	v_mov_b32_e32 v137, v131
	v_add_u32_e32 v138, v1, v184
	v_mov_b32_e32 v139, v131
	v_mov_b64_e32 v[140:141], 0x280
	v_mov_b64_e32 v[142:143], 0x27f
	v_add_u32_e32 v155, s71, v151
	v_add_u32_e32 v157, 0, v0
	v_add_u32_e32 v159, s72, v151
	s_mov_b64 s[10:11], 0x40000
	s_mov_b32 s73, 0x40000
	s_mov_b64 s[12:13], 0x48000
	s_mov_b32 s74, 0x48000
	s_mov_b64 s[14:15], 0x50000
	s_mov_b32 s75, 0x50000
	s_mov_b64 s[16:17], 0x58000
	s_mov_b32 s76, 0x58000
	s_barrier
.LBB0_831:
	s_add_i32 s33, s33, 1
	s_mul_i32 s8, s33, s65
	s_mul_hi_u32 s9, s33, s70
	s_add_i32 s9, s9, s8
	s_mul_i32 s8, s33, s70
	s_add_u32 s46, s8, s88
	s_addc_u32 s47, s9, s56
	v_cmp_gt_i64_e64 s[8:9], s[46:47], v[142:143]
	s_and_b64 vcc, exec, s[8:9]
	s_cbranch_vccnz .LBB0_833
	s_mul_i32 s25, s47, 0x66666667
	s_mul_hi_u32 s28, s46, 0x66666667
	s_mul_hi_u32 s24, s47, 0x66666667
	s_add_u32 s25, s25, s28
	s_mul_i32 s21, s46, 0x66666666
	s_addc_u32 s24, s24, 0
	s_mul_hi_u32 s20, s46, 0x66666666
	s_add_u32 s21, s21, s25
	s_addc_u32 s20, s20, 0
	s_add_u32 s20, s24, s20
	s_addc_u32 s21, 0, 0
	s_mul_i32 s25, s47, 0x66666666
	s_mul_hi_u32 s24, s47, 0x66666666
	s_add_u32 s20, s25, s20
	s_addc_u32 s21, s24, s21
	s_ashr_i32 s24, s47, 31
	s_mul_i32 s25, s24, 0x66666666
	s_mul_hi_u32 s28, s24, 0x66666667
	s_add_i32 s25, s28, s25
	s_mul_i32 s24, s24, 0x66666667
	s_add_i32 s25, s25, s24
	s_add_u32 s20, s20, s24
	s_addc_u32 s21, s21, s25
	s_lshr_b32 s24, s21, 31
	s_lshr_b64 s[20:21], s[20:21], 8
	s_add_i32 s20, s20, s24
	s_mul_i32 s21, s20, 0x280
	s_sub_i32 s21, s46, s21
	s_sext_i32_i16 s24, s21
	s_bfe_u32 s24, s24, 0x3001c
	s_add_i32 s24, s21, s24
	s_sext_i32_i16 s25, s24
	s_and_b32 s24, s24, 0xfff8
	s_sub_i32 s21, s21, s24
	s_ashr_i32 s25, s25, 3
	s_sext_i32_i16 s24, s21
	s_cmp_lt_i32 s24, 0
	s_cselect_b32 s24, s7, 0x50
	s_mul_i32 s21, s24, s21
	s_add_i32 s21, s21, s25
	s_sext_i32_i16 s24, s21
	s_bfe_u32 s24, s24, 0x5001a
	s_add_i32 s24, s21, s24
	s_sext_i32_i16 s25, s24
	s_and_b32 s24, s24, 0xffe0
	s_sub_i32 s21, s21, s24
	s_bfe_i32 s24, s21, 0x80000
	s_bfe_u32 s24, s24, 0x3000c
	s_add_i32 s24, s21, s24
	s_bfe_i32 s28, s24, 0x80000
	s_and_b32 s24, s24, 0xf8
	s_ashr_i32 s25, s25, 5
	s_sub_i32 s21, s21, s24
	s_lshl_b32 s25, s25, 3
	s_sext_i32_i16 s28, s28
	s_sext_i32_i8 s21, s21
	s_add_i32 s24, s25, s21
	s_ashr_i32 s44, s28, 3
